# SwiGLU epilogue: store address stepping moved from VALU (7 v_add_u32 per wave per tile) to SALU (store base stepped with s_add_u32/s_addc_u32 and restored at the end)
# speedup vs baseline: 1.0019x; 1.0003x over previous
; __device__ __forceinline__ unsigned cvt_pk_bf16(float lo, float hi) { unsigned r; asm volatile("v_cvt_pk_bf16_f32 %0, %1, %2" : "=v"(r) : "v"(lo), "v"(hi)); return r; }
; __device__ __forceinline__ float silu_f(float g) { return g * __builtin_amdgcn_rcpf(1.0f + __builtin_amdgcn_exp2f(g * -1.4426950408889634f)); }
;     __device__ __forceinline__ void operator()(const f32x4 (&acc)[2][2][4][2], const Unit& u, int wr, int wc, int fr, int fq) const {
;     ...
;             for (int m = 0; m < 4; ++m) { const int row = row0 + ai * HALF + m * 16; const float rs = rsv[ai][m];
;                 f32x4 g0 = acc[ai][0][m][0] * rs, g1 = acc[ai][0][m][1] * rs; const f32x4 t0 = acc[ai][1][m][0] * rs, t1 = acc[ai][1][m][1] * rs;
;                 if (silu) {
; #pragma unroll
;                     for (int j = 0; j < 4; ++j) { g0[j] = silu_f(g0[j]); g1[j] = silu_f(g1[j]); } }
;                 g0 = g0 * t0; g1 = g1 * t1;
;                 u32x4 w; w.x = cvt_pk_bf16(g0[0], g0[1]); w.y = cvt_pk_bf16(g0[2], g0[3]); w.z = cvt_pk_bf16(g1[0], g1[1]); w.w = cvt_pk_bf16(g1[2], g1[3]);
;                 *(u32x4*)(O + (size_t)row * ldc + col0 + (size_t)(row >> 12) * adj) = w; }
.Lep_have_rs:
	v_pk_mul_f32 v[146:147], v[142:143], v[240:241] op_sel_hi:[1,0]
	v_pk_mul_f32 v[148:149], v[144:145], v[240:241] op_sel_hi:[1,0]
	v_pk_mul_f32 v[150:151], v[138:139], v[240:241] op_sel_hi:[1,0]
	v_pk_mul_f32 v[152:153], v[140:141], v[240:241] op_sel_hi:[1,0]
	v_exp_f32_e32 v146, v146
	v_exp_f32_e32 v147, v147
	v_exp_f32_e32 v148, v148
	v_exp_f32_e32 v149, v149
	v_exp_f32_e32 v150, v150
	v_exp_f32_e32 v151, v151
	v_exp_f32_e32 v152, v152
	v_exp_f32_e32 v153, v153
	v_pk_mul_f32 v[142:143], v[142:143], v[130:131]
	v_pk_mul_f32 v[144:145], v[144:145], v[132:133]
	v_pk_mul_f32 v[138:139], v[138:139], v[126:127]
	v_pk_mul_f32 v[140:141], v[140:141], v[128:129]
	v_pk_fma_f32 v[146:147], v[146:147], v[240:241], v[240:241] op_sel:[0,1,1] op_sel_hi:[1,1,1]
	v_pk_fma_f32 v[148:149], v[148:149], v[240:241], v[240:241] op_sel:[0,1,1] op_sel_hi:[1,1,1]
	v_pk_fma_f32 v[150:151], v[150:151], v[240:241], v[240:241] op_sel:[0,1,1] op_sel_hi:[1,1,1]
	v_pk_fma_f32 v[152:153], v[152:153], v[240:241], v[240:241] op_sel:[0,1,1] op_sel_hi:[1,1,1]
	v_rcp_f32_e32 v146, v146
	v_rcp_f32_e32 v147, v147
	v_rcp_f32_e32 v148, v148
	v_rcp_f32_e32 v149, v149
	v_rcp_f32_e32 v150, v150
	v_rcp_f32_e32 v151, v151
	v_rcp_f32_e32 v152, v152
	v_rcp_f32_e32 v153, v153
	v_pk_mul_f32 v[154:155], v[122:123], v[242:243] op_sel_hi:[1,0]
	v_pk_mul_f32 v[156:157], v[124:125], v[242:243] op_sel_hi:[1,0]
	v_pk_mul_f32 v[158:159], v[118:119], v[242:243] op_sel_hi:[1,0]
	v_pk_mul_f32 v[160:161], v[120:121], v[242:243] op_sel_hi:[1,0]
	v_pk_mul_f32 v[142:143], v[142:143], v[146:147]
	v_pk_mul_f32 v[144:145], v[144:145], v[148:149]
	v_pk_mul_f32 v[138:139], v[138:139], v[150:151]
	v_pk_mul_f32 v[140:141], v[140:141], v[152:153]
	v_cvt_pk_bf16_f32 v162, v142, v143
	v_cvt_pk_bf16_f32 v163, v144, v145
	v_cvt_pk_bf16_f32 v164, v138, v139
	v_cvt_pk_bf16_f32 v165, v140, v141
	global_store_dwordx4 v190, v[162:165], s[10:11] sc1
	s_add_u32 s10, s10, s30
	s_addc_u32 s11, s11, 0
	v_exp_f32_e32 v154, v154
	v_exp_f32_e32 v155, v155
	v_exp_f32_e32 v156, v156
	v_exp_f32_e32 v157, v157
	v_exp_f32_e32 v158, v158
	v_exp_f32_e32 v159, v159
	v_exp_f32_e32 v160, v160
	v_exp_f32_e32 v161, v161
	v_pk_mul_f32 v[122:123], v[122:123], v[110:111]
	v_pk_mul_f32 v[124:125], v[124:125], v[112:113]
	v_pk_mul_f32 v[118:119], v[118:119], v[106:107]
	v_pk_mul_f32 v[120:121], v[120:121], v[108:109]
	v_pk_fma_f32 v[154:155], v[154:155], v[242:243], v[242:243] op_sel:[0,1,1] op_sel_hi:[1,1,1]
	v_pk_fma_f32 v[156:157], v[156:157], v[242:243], v[242:243] op_sel:[0,1,1] op_sel_hi:[1,1,1]
	v_pk_fma_f32 v[158:159], v[158:159], v[242:243], v[242:243] op_sel:[0,1,1] op_sel_hi:[1,1,1]
	v_pk_fma_f32 v[160:161], v[160:161], v[242:243], v[242:243] op_sel:[0,1,1] op_sel_hi:[1,1,1]
	v_rcp_f32_e32 v154, v154
	v_rcp_f32_e32 v155, v155
	v_rcp_f32_e32 v156, v156
	v_rcp_f32_e32 v157, v157
	v_rcp_f32_e32 v158, v158
	v_rcp_f32_e32 v159, v159
	v_rcp_f32_e32 v160, v160
	v_rcp_f32_e32 v161, v161
	v_pk_mul_f32 v[146:147], v[102:103], v[244:245] op_sel_hi:[1,0]
	v_pk_mul_f32 v[148:149], v[104:105], v[244:245] op_sel_hi:[1,0]
	v_pk_mul_f32 v[150:151], v[98:99], v[244:245] op_sel_hi:[1,0]
	v_pk_mul_f32 v[152:153], v[100:101], v[244:245] op_sel_hi:[1,0]
	v_pk_mul_f32 v[122:123], v[122:123], v[154:155]
	v_pk_mul_f32 v[124:125], v[124:125], v[156:157]
	v_pk_mul_f32 v[118:119], v[118:119], v[158:159]
	v_pk_mul_f32 v[120:121], v[120:121], v[160:161]
	v_cvt_pk_bf16_f32 v166, v122, v123
	v_cvt_pk_bf16_f32 v167, v124, v125
	v_cvt_pk_bf16_f32 v168, v118, v119
	v_cvt_pk_bf16_f32 v169, v120, v121
	global_store_dwordx4 v190, v[166:169], s[10:11] sc1
	s_add_u32 s10, s10, s30
	s_addc_u32 s11, s11, 0
	v_exp_f32_e32 v146, v146
	v_exp_f32_e32 v147, v147
	v_exp_f32_e32 v148, v148
	v_exp_f32_e32 v149, v149
	v_exp_f32_e32 v150, v150
	v_exp_f32_e32 v151, v151
	v_exp_f32_e32 v152, v152
	v_exp_f32_e32 v153, v153
	v_pk_mul_f32 v[102:103], v[102:103], v[90:91]
	v_pk_mul_f32 v[104:105], v[104:105], v[92:93]
	v_pk_mul_f32 v[98:99], v[98:99], v[86:87]
	v_pk_mul_f32 v[100:101], v[100:101], v[88:89]
	v_pk_fma_f32 v[146:147], v[146:147], v[244:245], v[244:245] op_sel:[0,1,1] op_sel_hi:[1,1,1]
	v_pk_fma_f32 v[148:149], v[148:149], v[244:245], v[244:245] op_sel:[0,1,1] op_sel_hi:[1,1,1]
	v_pk_fma_f32 v[150:151], v[150:151], v[244:245], v[244:245] op_sel:[0,1,1] op_sel_hi:[1,1,1]
	v_pk_fma_f32 v[152:153], v[152:153], v[244:245], v[244:245] op_sel:[0,1,1] op_sel_hi:[1,1,1]
	v_rcp_f32_e32 v146, v146
	v_rcp_f32_e32 v147, v147
	v_rcp_f32_e32 v148, v148
	v_rcp_f32_e32 v149, v149
	v_rcp_f32_e32 v150, v150
	v_rcp_f32_e32 v151, v151
	v_rcp_f32_e32 v152, v152
	v_rcp_f32_e32 v153, v153
	v_pk_mul_f32 v[154:155], v[82:83], v[246:247] op_sel_hi:[1,0]
	v_pk_mul_f32 v[156:157], v[84:85], v[246:247] op_sel_hi:[1,0]
	v_pk_mul_f32 v[158:159], v[78:79], v[246:247] op_sel_hi:[1,0]
	v_pk_mul_f32 v[160:161], v[80:81], v[246:247] op_sel_hi:[1,0]
	v_pk_mul_f32 v[102:103], v[102:103], v[146:147]
	v_pk_mul_f32 v[104:105], v[104:105], v[148:149]
	v_pk_mul_f32 v[98:99], v[98:99], v[150:151]
	v_pk_mul_f32 v[100:101], v[100:101], v[152:153]
	v_cvt_pk_bf16_f32 v162, v102, v103
	v_cvt_pk_bf16_f32 v163, v104, v105
	v_cvt_pk_bf16_f32 v164, v98, v99
	v_cvt_pk_bf16_f32 v165, v100, v101
	global_store_dwordx4 v190, v[162:165], s[10:11] sc1
	s_add_u32 s10, s10, s30
	s_addc_u32 s11, s11, 0
	v_exp_f32_e32 v154, v154
	v_exp_f32_e32 v155, v155
	v_exp_f32_e32 v156, v156
	v_exp_f32_e32 v157, v157
	v_exp_f32_e32 v158, v158
	v_exp_f32_e32 v159, v159
	v_exp_f32_e32 v160, v160
	v_exp_f32_e32 v161, v161
	v_pk_mul_f32 v[82:83], v[82:83], v[70:71]
	v_pk_mul_f32 v[84:85], v[84:85], v[72:73]
	v_pk_mul_f32 v[78:79], v[78:79], v[66:67]
; __device__ __forceinline__ unsigned cvt_pk_bf16(float lo, float hi) { unsigned r; asm volatile("v_cvt_pk_bf16_f32 %0, %1, %2" : "=v"(r) : "v"(lo), "v"(hi)); return r; }
; __device__ __forceinline__ float silu_f(float g) { return g * __builtin_amdgcn_rcpf(1.0f + __builtin_amdgcn_exp2f(g * -1.4426950408889634f)); }
;     __device__ __forceinline__ void operator()(const f32x4 (&acc)[2][2][4][2], const Unit& u, int wr, int wc, int fr, int fq) const {
;     ...
;             for (int m = 0; m < 4; ++m) { const int row = row0 + ai * HALF + m * 16; const float rs = rsv[ai][m];
;                 f32x4 g0 = acc[ai][0][m][0] * rs, g1 = acc[ai][0][m][1] * rs; const f32x4 t0 = acc[ai][1][m][0] * rs, t1 = acc[ai][1][m][1] * rs;
;                 if (silu) {
; #pragma unroll
;                     for (int j = 0; j < 4; ++j) { g0[j] = silu_f(g0[j]); g1[j] = silu_f(g1[j]); } }
;                 g0 = g0 * t0; g1 = g1 * t1;
;                 u32x4 w; w.x = cvt_pk_bf16(g0[0], g0[1]); w.y = cvt_pk_bf16(g0[2], g0[3]); w.z = cvt_pk_bf16(g1[0], g1[1]); w.w = cvt_pk_bf16(g1[2], g1[3]);
;                 *(u32x4*)(O + (size_t)row * ldc + col0 + (size_t)(row >> 12) * adj) = w; }
	v_pk_mul_f32 v[80:81], v[80:81], v[68:69]
	v_pk_fma_f32 v[154:155], v[154:155], v[246:247], v[246:247] op_sel:[0,1,1] op_sel_hi:[1,1,1]
	v_pk_fma_f32 v[156:157], v[156:157], v[246:247], v[246:247] op_sel:[0,1,1] op_sel_hi:[1,1,1]
	v_pk_fma_f32 v[158:159], v[158:159], v[246:247], v[246:247] op_sel:[0,1,1] op_sel_hi:[1,1,1]
	v_pk_fma_f32 v[160:161], v[160:161], v[246:247], v[246:247] op_sel:[0,1,1] op_sel_hi:[1,1,1]
	v_rcp_f32_e32 v154, v154
	v_rcp_f32_e32 v155, v155
	v_rcp_f32_e32 v156, v156
	v_rcp_f32_e32 v157, v157
	v_rcp_f32_e32 v158, v158
	v_rcp_f32_e32 v159, v159
	v_rcp_f32_e32 v160, v160
	v_rcp_f32_e32 v161, v161
	v_pk_mul_f32 v[146:147], v[62:63], v[248:249] op_sel_hi:[1,0]
	v_pk_mul_f32 v[148:149], v[64:65], v[248:249] op_sel_hi:[1,0]
	v_pk_mul_f32 v[150:151], v[58:59], v[248:249] op_sel_hi:[1,0]
	v_pk_mul_f32 v[152:153], v[60:61], v[248:249] op_sel_hi:[1,0]
	v_pk_mul_f32 v[82:83], v[82:83], v[154:155]
	v_pk_mul_f32 v[84:85], v[84:85], v[156:157]
	v_pk_mul_f32 v[78:79], v[78:79], v[158:159]
	v_pk_mul_f32 v[80:81], v[80:81], v[160:161]
	v_cvt_pk_bf16_f32 v166, v82, v83
	v_cvt_pk_bf16_f32 v167, v84, v85
	v_cvt_pk_bf16_f32 v168, v78, v79
	v_cvt_pk_bf16_f32 v169, v80, v81
	global_store_dwordx4 v190, v[166:169], s[10:11] sc1
	s_add_u32 s10, s10, s31
	s_addc_u32 s11, s11, 0
	v_exp_f32_e32 v146, v146
	v_exp_f32_e32 v147, v147
	v_exp_f32_e32 v148, v148
	v_exp_f32_e32 v149, v149
	v_exp_f32_e32 v150, v150
	v_exp_f32_e32 v151, v151
	v_exp_f32_e32 v152, v152
	v_exp_f32_e32 v153, v153
	v_pk_mul_f32 v[62:63], v[62:63], v[54:55]
	v_pk_mul_f32 v[64:65], v[64:65], v[56:57]
	v_pk_mul_f32 v[58:59], v[58:59], v[50:51]
	v_pk_mul_f32 v[60:61], v[60:61], v[52:53]
	v_pk_fma_f32 v[146:147], v[146:147], v[248:249], v[248:249] op_sel:[0,1,1] op_sel_hi:[1,1,1]
	v_pk_fma_f32 v[148:149], v[148:149], v[248:249], v[248:249] op_sel:[0,1,1] op_sel_hi:[1,1,1]
	v_pk_fma_f32 v[150:151], v[150:151], v[248:249], v[248:249] op_sel:[0,1,1] op_sel_hi:[1,1,1]
	v_pk_fma_f32 v[152:153], v[152:153], v[248:249], v[248:249] op_sel:[0,1,1] op_sel_hi:[1,1,1]
	v_rcp_f32_e32 v146, v146
	v_rcp_f32_e32 v147, v147
	v_rcp_f32_e32 v148, v148
	v_rcp_f32_e32 v149, v149
	v_rcp_f32_e32 v150, v150
	v_rcp_f32_e32 v151, v151
	v_rcp_f32_e32 v152, v152
	v_rcp_f32_e32 v153, v153
	v_pk_mul_f32 v[154:155], v[46:47], v[250:251] op_sel_hi:[1,0]
	v_pk_mul_f32 v[156:157], v[48:49], v[250:251] op_sel_hi:[1,0]
	v_pk_mul_f32 v[158:159], v[42:43], v[250:251] op_sel_hi:[1,0]
	v_pk_mul_f32 v[160:161], v[44:45], v[250:251] op_sel_hi:[1,0]
	v_pk_mul_f32 v[62:63], v[62:63], v[146:147]
	v_pk_mul_f32 v[64:65], v[64:65], v[148:149]
	v_pk_mul_f32 v[58:59], v[58:59], v[150:151]
	v_pk_mul_f32 v[60:61], v[60:61], v[152:153]
	v_cvt_pk_bf16_f32 v162, v62, v63
	v_cvt_pk_bf16_f32 v163, v64, v65
	v_cvt_pk_bf16_f32 v164, v58, v59
	v_cvt_pk_bf16_f32 v165, v60, v61
	global_store_dwordx4 v190, v[162:165], s[10:11] sc1
	s_add_u32 s10, s10, s30
	s_addc_u32 s11, s11, 0
	v_exp_f32_e32 v154, v154
	v_exp_f32_e32 v155, v155
	v_exp_f32_e32 v156, v156
	v_exp_f32_e32 v157, v157
	v_exp_f32_e32 v158, v158
	v_exp_f32_e32 v159, v159
	v_exp_f32_e32 v160, v160
	v_exp_f32_e32 v161, v161
	v_pk_mul_f32 v[46:47], v[46:47], v[38:39]
	v_pk_mul_f32 v[48:49], v[48:49], v[40:41]
	v_pk_mul_f32 v[42:43], v[42:43], v[34:35]
	v_pk_mul_f32 v[44:45], v[44:45], v[36:37]
	v_pk_fma_f32 v[154:155], v[154:155], v[250:251], v[250:251] op_sel:[0,1,1] op_sel_hi:[1,1,1]
	v_pk_fma_f32 v[156:157], v[156:157], v[250:251], v[250:251] op_sel:[0,1,1] op_sel_hi:[1,1,1]
	v_pk_fma_f32 v[158:159], v[158:159], v[250:251], v[250:251] op_sel:[0,1,1] op_sel_hi:[1,1,1]
	v_pk_fma_f32 v[160:161], v[160:161], v[250:251], v[250:251] op_sel:[0,1,1] op_sel_hi:[1,1,1]
	v_rcp_f32_e32 v154, v154
	v_rcp_f32_e32 v155, v155
	v_rcp_f32_e32 v156, v156
	v_rcp_f32_e32 v157, v157
	v_rcp_f32_e32 v158, v158
	v_rcp_f32_e32 v159, v159
; __device__ __forceinline__ unsigned cvt_pk_bf16(float lo, float hi) { unsigned r; asm volatile("v_cvt_pk_bf16_f32 %0, %1, %2" : "=v"(r) : "v"(lo), "v"(hi)); return r; }
; __device__ __forceinline__ float silu_f(float g) { return g * __builtin_amdgcn_rcpf(1.0f + __builtin_amdgcn_exp2f(g * -1.4426950408889634f)); }
;     __device__ __forceinline__ void operator()(const f32x4 (&acc)[2][2][4][2], const Unit& u, int wr, int wc, int fr, int fq) const {
;     ...
;             for (int m = 0; m < 4; ++m) { const int row = row0 + ai * HALF + m * 16; const float rs = rsv[ai][m];
;                 f32x4 g0 = acc[ai][0][m][0] * rs, g1 = acc[ai][0][m][1] * rs; const f32x4 t0 = acc[ai][1][m][0] * rs, t1 = acc[ai][1][m][1] * rs;
;                 if (silu) {
; #pragma unroll
;                     for (int j = 0; j < 4; ++j) { g0[j] = silu_f(g0[j]); g1[j] = silu_f(g1[j]); } }
;                 g0 = g0 * t0; g1 = g1 * t1;
;                 u32x4 w; w.x = cvt_pk_bf16(g0[0], g0[1]); w.y = cvt_pk_bf16(g0[2], g0[3]); w.z = cvt_pk_bf16(g1[0], g1[1]); w.w = cvt_pk_bf16(g1[2], g1[3]);
;                 *(u32x4*)(O + (size_t)row * ldc + col0 + (size_t)(row >> 12) * adj) = w; }
;     }
	v_rcp_f32_e32 v160, v160
	v_rcp_f32_e32 v161, v161
	v_pk_mul_f32 v[146:147], v[30:31], v[252:253] op_sel_hi:[1,0]
	v_pk_mul_f32 v[148:149], v[32:33], v[252:253] op_sel_hi:[1,0]
	v_pk_mul_f32 v[150:151], v[26:27], v[252:253] op_sel_hi:[1,0]
	v_pk_mul_f32 v[152:153], v[28:29], v[252:253] op_sel_hi:[1,0]
	v_pk_mul_f32 v[46:47], v[46:47], v[154:155]
	v_pk_mul_f32 v[48:49], v[48:49], v[156:157]
	v_pk_mul_f32 v[42:43], v[42:43], v[158:159]
	v_pk_mul_f32 v[44:45], v[44:45], v[160:161]
	v_cvt_pk_bf16_f32 v166, v46, v47
	v_cvt_pk_bf16_f32 v167, v48, v49
	v_cvt_pk_bf16_f32 v168, v42, v43
	v_cvt_pk_bf16_f32 v169, v44, v45
	global_store_dwordx4 v190, v[166:169], s[10:11] sc1
	s_add_u32 s10, s10, s30
	s_addc_u32 s11, s11, 0
	v_exp_f32_e32 v146, v146
	v_exp_f32_e32 v147, v147
	v_exp_f32_e32 v148, v148
	v_exp_f32_e32 v149, v149
	v_exp_f32_e32 v150, v150
	v_exp_f32_e32 v151, v151
	v_exp_f32_e32 v152, v152
	v_exp_f32_e32 v153, v153
	v_pk_mul_f32 v[30:31], v[30:31], v[22:23]
	v_pk_mul_f32 v[32:33], v[32:33], v[24:25]
	v_pk_mul_f32 v[26:27], v[26:27], v[18:19]
	v_pk_mul_f32 v[28:29], v[28:29], v[20:21]
	v_pk_fma_f32 v[146:147], v[146:147], v[252:253], v[252:253] op_sel:[0,1,1] op_sel_hi:[1,1,1]
	v_pk_fma_f32 v[148:149], v[148:149], v[252:253], v[252:253] op_sel:[0,1,1] op_sel_hi:[1,1,1]
	v_pk_fma_f32 v[150:151], v[150:151], v[252:253], v[252:253] op_sel:[0,1,1] op_sel_hi:[1,1,1]
	v_pk_fma_f32 v[152:153], v[152:153], v[252:253], v[252:253] op_sel:[0,1,1] op_sel_hi:[1,1,1]
	v_rcp_f32_e32 v146, v146
	v_rcp_f32_e32 v147, v147
	v_rcp_f32_e32 v148, v148
	v_rcp_f32_e32 v149, v149
	v_rcp_f32_e32 v150, v150
	v_rcp_f32_e32 v151, v151
	v_rcp_f32_e32 v152, v152
	v_rcp_f32_e32 v153, v153
	v_pk_mul_f32 v[154:155], v[14:15], v[214:215] op_sel_hi:[1,0]
	v_pk_mul_f32 v[156:157], v[16:17], v[214:215] op_sel_hi:[1,0]
	v_pk_mul_f32 v[158:159], v[10:11], v[214:215] op_sel_hi:[1,0]
	v_pk_mul_f32 v[160:161], v[12:13], v[214:215] op_sel_hi:[1,0]
	v_pk_mul_f32 v[30:31], v[30:31], v[146:147]
	v_pk_mul_f32 v[32:33], v[32:33], v[148:149]
	v_pk_mul_f32 v[26:27], v[26:27], v[150:151]
	v_pk_mul_f32 v[28:29], v[28:29], v[152:153]
	v_cvt_pk_bf16_f32 v162, v30, v31
	v_cvt_pk_bf16_f32 v163, v32, v33
	v_cvt_pk_bf16_f32 v164, v26, v27
	v_cvt_pk_bf16_f32 v165, v28, v29
	global_store_dwordx4 v190, v[162:165], s[10:11] sc1
	s_add_u32 s10, s10, s30
	s_addc_u32 s11, s11, 0
	v_exp_f32_e32 v154, v154
	v_exp_f32_e32 v155, v155
	v_exp_f32_e32 v156, v156
	v_exp_f32_e32 v157, v157
	v_exp_f32_e32 v158, v158
	v_exp_f32_e32 v159, v159
	v_exp_f32_e32 v160, v160
	v_exp_f32_e32 v161, v161
	v_pk_mul_f32 v[14:15], v[14:15], v[6:7]
	v_pk_mul_f32 v[16:17], v[16:17], v[8:9]
	v_pk_mul_f32 v[10:11], v[10:11], v[2:3]
	v_pk_mul_f32 v[12:13], v[12:13], v[4:5]
	v_pk_fma_f32 v[154:155], v[154:155], v[214:215], v[214:215] op_sel:[0,1,1] op_sel_hi:[1,1,1]
	v_pk_fma_f32 v[156:157], v[156:157], v[214:215], v[214:215] op_sel:[0,1,1] op_sel_hi:[1,1,1]
	v_pk_fma_f32 v[158:159], v[158:159], v[214:215], v[214:215] op_sel:[0,1,1] op_sel_hi:[1,1,1]
	v_pk_fma_f32 v[160:161], v[160:161], v[214:215], v[214:215] op_sel:[0,1,1] op_sel_hi:[1,1,1]
	v_rcp_f32_e32 v154, v154
	v_rcp_f32_e32 v155, v155
	v_rcp_f32_e32 v156, v156
	v_rcp_f32_e32 v157, v157
	v_rcp_f32_e32 v158, v158
	v_rcp_f32_e32 v159, v159
	v_rcp_f32_e32 v160, v160
	v_rcp_f32_e32 v161, v161
	v_pk_mul_f32 v[14:15], v[14:15], v[154:155]
	v_pk_mul_f32 v[16:17], v[16:17], v[156:157]
	v_pk_mul_f32 v[10:11], v[10:11], v[158:159]
	v_pk_mul_f32 v[12:13], v[12:13], v[160:161]
	v_cvt_pk_bf16_f32 v166, v14, v15
	v_cvt_pk_bf16_f32 v167, v16, v17
	v_cvt_pk_bf16_f32 v168, v10, v11
	v_cvt_pk_bf16_f32 v169, v12, v13
	global_store_dwordx4 v190, v[166:169], s[10:11] sc1
	s_mul_i32 s4, s30, 6
	s_add_i32 s4, s4, s31
	s_sub_u32 s10, s10, s4
	s_subb_u32 s11, s11, 0
	s_andn2_b64 vcc, exec, s[8:9]
	s_mov_b64 s[4:5], -1
	s_branch .Lep_join
